# static priority raise for waves 4-7 also during the ssd_s3 item (in addition to the selected-attention loop)
# speedup vs baseline: 1.0189x; 1.0189x over previous
.LBB0_2256:
	v_readlane_b32 s4, v243, 30
	v_readlane_b32 s5, v243, 31
	s_andn2_b64 vcc, exec, s[4:5]
	s_barrier
	s_cbranch_vccnz .LBB0_2363
	v_readfirstlane_b32 s2, v180
	s_bitcmp1_b32 s2, 8
	s_cbranch_scc0 .Ls3_prio_skip
	s_setprio 2
.Ls3_prio_skip:
	v_lshlrev_b32_e32 v124, 2, v180
	v_readlane_b32 s2, v242, 4
	v_bfe_u32 v3, v180, 4, 2
	v_ashrrev_i32_e32 v68, 4, v180
	v_add_u32_e32 v125, s2, v124
	s_movk_i32 s2, 0x280
	v_cmp_gt_i32_e64 s[6:7], s2, v180
	s_movk_i32 s2, 0x100
	v_max_i32_e32 v7, 0x80, v180
	v_cmp_gt_i32_e64 s[8:9], s2, v68
	v_lshlrev_b32_e32 v2, 3, v3
	v_readlane_b32 s2, v242, 7
	v_sub_u32_e32 v7, v7, v180
	v_add_u32_e32 v7, 0x1ff, v7
	v_add_u32_e32 v70, s2, v2
	s_movk_i32 s2, 0x1ff
	v_and_b32_e32 v71, 15, v180
	v_lshrrev_b32_e32 v9, 9, v7
	v_cmp_lt_u32_e64 s[12:13], s2, v7
	s_movk_i32 s2, 0x110
	v_lshlrev_b32_e32 v130, 5, v3
	v_readlane_b32 s5, v242, 6
	v_add_u32_e32 v9, 1, v9
	v_mul_lo_u32 v7, v68, s2
	v_lshlrev_b32_e32 v72, 4, v71
	v_add_u32_e32 v131, s5, v130
	v_lshlrev_b32_e32 v4, 7, v71
	v_and_b32_e32 v133, 0xfffffe, v9
	v_add_u32_e32 v135, s5, v124
	v_add3_u32 v136, v7, v72, 0
	v_mul_lo_u32 v7, v68, s81
	v_readlane_b32 s5, v242, 8
	v_ashrrev_i32_e32 v67, 6, v180
	v_ashrrev_i32_e32 v64, 8, v180
	v_readlane_b32 s4, v242, 5
	v_and_b32_e32 v127, 0x7f, v180
	v_mul_i32_i24_e32 v5, -14, v71
	v_lshlrev_b32_e32 v132, 2, v3
	v_or_b32_e32 v6, 0x800, v4
	v_or_b32_e32 v8, 0x1000, v4
	v_or_b32_e32 v10, 0x1800, v4
	v_cmp_ne_u32_e64 s[14:15], v9, v133
	v_add3_u32 v137, v7, v72, s5
	v_and_b32_e32 v7, 0x400, v4
	v_lshlrev_b32_e32 v9, 2, v68
	v_lshlrev_b32_e32 v139, 4, v3
	v_mul_u32_u24_e32 v3, 0x420, v3
	v_readlane_b32 s34, v243, 56
	v_and_b32_e32 v66, 0xff, v180
	v_ashrrev_i32_e32 v65, 31, v64
	v_add_u32_e32 v126, s4, v124
	v_or_b32_e32 v128, 0x200, v127
	v_lshlrev_b32_e32 v129, 3, v71
	v_cmp_gt_i32_e64 s[10:11], 16, v67
	v_lshl_add_u32 v134, v133, 9, v180
	v_add_u32_e32 v181, 0x200, v180
	v_mov_b32_e32 v73, v11
	v_ashrrev_i32_e32 v69, 31, v68
	v_add3_u32 v138, v7, v9, s4
	v_mad_u32_u24 v140, v71, s2, v139
	v_or_b32_e32 v141, 19, v132
	v_add3_u32 v142, v5, v3, v72
	v_lshlrev_b32_e32 v74, 1, v4
	v_lshlrev_b32_e32 v76, 1, v6
	v_lshlrev_b32_e32 v78, 1, v8
	v_lshlrev_b32_e32 v80, 1, v10
	v_lshlrev_b32_e32 v82, 1, v2
	v_readlane_b32 s35, v243, 57
	s_mov_b32 s2, s73
	s_branch .LBB0_2259
